# v30 + end-of-compute-segment s_barrier issued 2 MFMAs early (prio 2 for the trailing pair) in the three generic GEMM loops
# speedup vs baseline: 1.0161x; 1.0161x over previous
; #define PG8_STAGE(bufoff, gbase, voff) do { _Pragma("unroll") for (int _i = 0; _i < 2; ++_i) \
;         __builtin_amdgcn_global_load_lds((const unsigned*)((const char*)(gbase) + (voff)[_i]), (LAS unsigned*)(lds + (bufoff) + ldsw + _i * 8192), 16, 0, 0); } while (0)
; #define PG8_LDA(dst, b, h) do { _Pragma("unroll") for (int m = 0; m < 4; ++m) _Pragma("unroll") for (int k = 0; k < 2; ++k) dst[m][k] = *(const LAS bf16x8*)(lds + PG8_SA(b, h) + aoff + m * 2048 + k * 1024); } while (0)
; #define PG8_LDB(dst, b, h) do { _Pragma("unroll") for (int n = 0; n < 2; ++n) _Pragma("unroll") for (int k = 0; k < 2; ++k) dst[n][k] = *(const LAS bf16x8*)(lds + PG8_SB(b, h) + boff + n * 2048 + k * 1024); } while (0)
; #define PG8_MMA(ai, bj, At, Bt) do { __builtin_amdgcn_s_setprio(1); _Pragma("unroll") for (int m = 0; m < 4; ++m) _Pragma("unroll") for (int n = 0; n < 2; ++n) _Pragma("unroll") for (int k = 0; k < 2; ++k) \
;         acc[ai][bj][m][n] = __builtin_amdgcn_mfma_f32_16x16x32_bf16(Bt[n][k], At[m][k], acc[ai][bj][m][n], 0, 0, 0); __builtin_amdgcn_s_setprio(0); } while (0)
; #define PG8_WAIT_V(n) asm volatile("s_waitcnt vmcnt(" #n ")" ::: "memory")
; #define PG8_WAIT_L(n) asm volatile("s_waitcnt lgkmcnt(" #n ")" ::: "memory")
; #define PG8_BAR __builtin_amdgcn_s_barrier()
; #define PG8_SCHED __builtin_amdgcn_sched_barrier(0)
; template <class Epi, class Sched>
; __device__ __forceinline__ void gemm_phase(LAS unsigned char* lds, const Gemm g, Sched S, const Epi& E) {
;     ...
;         for (int t = 0; t < nt; t += 2) {
;             const bool last = (t == nt - 2);
;             const char* a1 = cA + (size_t)(t + 1) * kstep;
;             const char* a2 = last ? nA : cA + (size_t)(t + 2) * kstep; const char* b2 = last ? nB : cB + (size_t)(t + 2) * kstep;
;             const char* a3 = a2 + kstep; const char* b3 = b2 + kstep;
;             PG8_LDB(B0, 0, 0); PG8_LDB(B1, 0, 1); PG8_SCHED; PG8_LDA(At, 0, 0); PG8_STAGE(PG8_SA(1, 1), a1 + hstepA, voffA);
;             PG8_WAIT_V(8); PG8_WAIT_L(0); PG8_BAR; PG8_MMA(0, 0, At, B0); PG8_MMA(0, 1, At, B1); PG8_BAR; PG8_SCHED;
;             PG8_LDA(At, 0, 1); PG8_STAGE(PG8_SB(0, 0), b2, voffB); PG8_STAGE(PG8_SB(0, 1), b2 + hstepB, voffB); PG8_STAGE(PG8_SA(0, 0), a2, voffA);
;             PG8_WAIT_V(8); PG8_WAIT_L(0); PG8_BAR; PG8_MMA(1, 0, At, B0); PG8_MMA(1, 1, At, B1); PG8_BAR; PG8_SCHED;
.LBB0_630:
	s_add_i32 s67, s65, 2
	s_add_u32 s2, s0, 0xfffc0080
	s_addc_u32 s3, s1, -1
	s_add_i32 s99, 0, 0x10000
	s_cmp_eq_u32 s70, s65
	s_cselect_b32 vcc_hi, s55, s3
	s_cselect_b32 vcc_lo, s54, s2
	s_cselect_b32 s77, s45, s64
	s_cselect_b32 s76, s44, s63
	s_add_i32 s65, 0, 0x14000
	v_add_u32_e32 v142, s99, v180
	v_add_u32_e32 v158, s65, v180
	ds_read_b128 v[130:133], v142
	ds_read_b128 v[134:137], v142 offset:1024
	ds_read_b128 v[138:141], v142 offset:2048
	ds_read_b128 v[142:145], v142 offset:3072
	ds_read_b128 v[146:149], v158
	ds_read_b128 v[150:153], v158 offset:1024
	ds_read_b128 v[154:157], v158 offset:2048
	ds_read_b128 v[158:161], v158 offset:3072
	s_add_i32 m0, s53, 0xc000
	ds_read_b128 v[174:177], v191
	ds_read_b128 v[192:195], v191 offset:1024
	ds_read_b128 v[196:199], v191 offset:2048
	ds_read_b128 v[200:203], v191 offset:3072
	ds_read_b128 v[204:207], v191 offset:4096
	ds_read_b128 v[208:211], v191 offset:5120
	ds_read_b128 v[212:215], v191 offset:6144
	ds_read_b128 v[216:219], v191 offset:7168
	global_load_lds_dwordx4 v172, s[0:1]
	s_add_i32 m0, s53, 0xe000
	s_nop 0
	global_load_lds_dwordx4 v170, s[0:1]
	s_waitcnt vmcnt(8)
	s_waitcnt lgkmcnt(0)
	s_barrier
	s_setprio 1
	s_waitcnt lgkmcnt(0)
	v_mfma_f32_16x16x32_bf16 v[126:129], v[130:133], v[174:177], v[126:129]
	v_mfma_f32_16x16x32_bf16 v[122:125], v[138:141], v[174:177], v[122:125]
	v_mfma_f32_16x16x32_bf16 v[114:117], v[130:133], v[196:199], v[114:117]
	v_mfma_f32_16x16x32_bf16 v[106:109], v[138:141], v[196:199], v[106:109]
	v_mfma_f32_16x16x32_bf16 v[98:101], v[130:133], v[204:207], v[98:101]
	v_mfma_f32_16x16x32_bf16 v[90:93], v[138:141], v[204:207], v[90:93]
	v_mfma_f32_16x16x32_bf16 v[82:85], v[130:133], v[212:215], v[82:85]
	v_mfma_f32_16x16x32_bf16 v[74:77], v[138:141], v[212:215], v[74:77]
	v_mfma_f32_16x16x32_bf16 v[126:129], v[134:137], v[192:195], v[126:129]
	v_mfma_f32_16x16x32_bf16 v[122:125], v[142:145], v[192:195], v[122:125]
	v_mfma_f32_16x16x32_bf16 v[114:117], v[134:137], v[200:203], v[114:117]
	v_mfma_f32_16x16x32_bf16 v[106:109], v[142:145], v[200:203], v[106:109]
	v_mfma_f32_16x16x32_bf16 v[98:101], v[134:137], v[208:211], v[98:101]
	v_mfma_f32_16x16x32_bf16 v[90:93], v[142:145], v[208:211], v[90:93]
	v_mfma_f32_16x16x32_bf16 v[82:85], v[134:137], v[216:219], v[82:85]
	v_mfma_f32_16x16x32_bf16 v[74:77], v[142:145], v[216:219], v[74:77]
	s_setprio 0
	s_setprio 1
	v_mfma_f32_16x16x32_bf16 v[118:121], v[146:149], v[174:177], v[118:121]
	v_mfma_f32_16x16x32_bf16 v[110:113], v[154:157], v[174:177], v[110:113]
	v_mfma_f32_16x16x32_bf16 v[102:105], v[146:149], v[196:199], v[102:105]
	v_mfma_f32_16x16x32_bf16 v[94:97], v[154:157], v[196:199], v[94:97]
	v_mfma_f32_16x16x32_bf16 v[86:89], v[146:149], v[204:207], v[86:89]
	v_mfma_f32_16x16x32_bf16 v[78:81], v[154:157], v[204:207], v[78:81]
	v_mfma_f32_16x16x32_bf16 v[70:73], v[146:149], v[212:215], v[70:73]
	v_mfma_f32_16x16x32_bf16 v[66:69], v[154:157], v[212:215], v[66:69]
	v_mfma_f32_16x16x32_bf16 v[118:121], v[150:153], v[192:195], v[118:121]
	v_mfma_f32_16x16x32_bf16 v[110:113], v[158:161], v[192:195], v[110:113]
	v_mfma_f32_16x16x32_bf16 v[102:105], v[150:153], v[200:203], v[102:105]
	v_mfma_f32_16x16x32_bf16 v[94:97], v[158:161], v[200:203], v[94:97]
	v_mfma_f32_16x16x32_bf16 v[86:89], v[150:153], v[208:211], v[86:89]
	v_mfma_f32_16x16x32_bf16 v[78:81], v[158:161], v[208:211], v[78:81]
	s_setprio 2
	s_barrier
	v_mfma_f32_16x16x32_bf16 v[70:73], v[150:153], v[216:219], v[70:73]
	v_mfma_f32_16x16x32_bf16 v[66:69], v[158:161], v[216:219], v[66:69]
	s_setprio 0
	s_add_i32 s2, s99, s43
	s_mov_b32 m0, s2
	ds_read_b128 v[174:177], v191 offset:16384
	ds_read_b128 v[192:195], v191 offset:17408
	ds_read_b128 v[196:199], v191 offset:18432
	ds_read_b128 v[200:203], v191 offset:19456
	ds_read_b128 v[204:207], v191 offset:20480
	ds_read_b128 v[208:211], v191 offset:21504
	ds_read_b128 v[212:215], v191 offset:22528
	ds_read_b128 v[216:219], v191 offset:23552
	global_load_lds_dwordx4 v0, s[76:77]
	s_add_i32 m0, s2, 0x2000
	s_add_u32 s2, s76, 0x40000
	s_addc_u32 s3, s77, 0
	s_add_i32 s65, s65, s43
	global_load_lds_dwordx4 v168, s[76:77]
	s_mov_b32 m0, s65
	s_nop 0
	global_load_lds_dwordx4 v0, s[2:3]
	s_add_i32 m0, s65, 0x2000
	s_nop 0
	global_load_lds_dwordx4 v168, s[2:3]
	s_mov_b32 m0, s53
	s_nop 0
	global_load_lds_dwordx4 v164, vcc
	s_mov_b32 m0, s85
	s_nop 0
	global_load_lds_dwordx4 v166, vcc
	s_waitcnt vmcnt(8)
	s_waitcnt lgkmcnt(0)
	s_barrier
	s_setprio 1
	s_waitcnt lgkmcnt(0)
	v_mfma_f32_16x16x32_bf16 v[62:65], v[130:133], v[174:177], v[62:65]
	v_mfma_f32_16x16x32_bf16 v[58:61], v[138:141], v[174:177], v[58:61]
	v_mfma_f32_16x16x32_bf16 v[50:53], v[130:133], v[196:199], v[50:53]
	v_mfma_f32_16x16x32_bf16 v[42:45], v[138:141], v[196:199], v[42:45]
	v_mfma_f32_16x16x32_bf16 v[34:37], v[130:133], v[204:207], v[34:37]
	v_mfma_f32_16x16x32_bf16 v[26:29], v[138:141], v[204:207], v[26:29]
	v_mfma_f32_16x16x32_bf16 v[18:21], v[130:133], v[212:215], v[18:21]
	v_mfma_f32_16x16x32_bf16 v[10:13], v[138:141], v[212:215], v[10:13]
	v_mfma_f32_16x16x32_bf16 v[62:65], v[134:137], v[192:195], v[62:65]
	v_mfma_f32_16x16x32_bf16 v[58:61], v[142:145], v[192:195], v[58:61]
	v_mfma_f32_16x16x32_bf16 v[50:53], v[134:137], v[200:203], v[50:53]
	v_mfma_f32_16x16x32_bf16 v[42:45], v[142:145], v[200:203], v[42:45]
	v_mfma_f32_16x16x32_bf16 v[34:37], v[134:137], v[208:211], v[34:37]
	v_mfma_f32_16x16x32_bf16 v[26:29], v[142:145], v[208:211], v[26:29]
	v_mfma_f32_16x16x32_bf16 v[18:21], v[134:137], v[216:219], v[18:21]
	v_mfma_f32_16x16x32_bf16 v[10:13], v[142:145], v[216:219], v[10:13]
	s_setprio 0
	s_setprio 1
	v_mfma_f32_16x16x32_bf16 v[54:57], v[146:149], v[174:177], v[54:57]
	v_mfma_f32_16x16x32_bf16 v[46:49], v[154:157], v[174:177], v[46:49]
	v_mfma_f32_16x16x32_bf16 v[38:41], v[146:149], v[196:199], v[38:41]
	v_mfma_f32_16x16x32_bf16 v[30:33], v[154:157], v[196:199], v[30:33]
	v_mfma_f32_16x16x32_bf16 v[22:25], v[146:149], v[204:207], v[22:25]
	v_mfma_f32_16x16x32_bf16 v[14:17], v[154:157], v[204:207], v[14:17]
	v_mfma_f32_16x16x32_bf16 v[6:9], v[146:149], v[212:215], v[6:9]
	v_mfma_f32_16x16x32_bf16 v[2:5], v[154:157], v[212:215], v[2:5]
	v_mfma_f32_16x16x32_bf16 v[54:57], v[150:153], v[192:195], v[54:57]
	v_mfma_f32_16x16x32_bf16 v[46:49], v[158:161], v[192:195], v[46:49]
	v_mfma_f32_16x16x32_bf16 v[38:41], v[150:153], v[200:203], v[38:41]
	v_mfma_f32_16x16x32_bf16 v[30:33], v[158:161], v[200:203], v[30:33]
	v_mfma_f32_16x16x32_bf16 v[22:25], v[150:153], v[208:211], v[22:25]
	v_mfma_f32_16x16x32_bf16 v[14:17], v[158:161], v[208:211], v[14:17]
	s_setprio 2
	s_barrier
; #define PG8_STAGE(bufoff, gbase, voff) do { _Pragma("unroll") for (int _i = 0; _i < 2; ++_i) \
;         __builtin_amdgcn_global_load_lds((const unsigned*)((const char*)(gbase) + (voff)[_i]), (LAS unsigned*)(lds + (bufoff) + ldsw + _i * 8192), 16, 0, 0); } while (0)
; #define PG8_LDA(dst, b, h) do { _Pragma("unroll") for (int m = 0; m < 4; ++m) _Pragma("unroll") for (int k = 0; k < 2; ++k) dst[m][k] = *(const LAS bf16x8*)(lds + PG8_SA(b, h) + aoff + m * 2048 + k * 1024); } while (0)
; #define PG8_LDB(dst, b, h) do { _Pragma("unroll") for (int n = 0; n < 2; ++n) _Pragma("unroll") for (int k = 0; k < 2; ++k) dst[n][k] = *(const LAS bf16x8*)(lds + PG8_SB(b, h) + boff + n * 2048 + k * 1024); } while (0)
; #define PG8_MMA(ai, bj, At, Bt) do { __builtin_amdgcn_s_setprio(1); _Pragma("unroll") for (int m = 0; m < 4; ++m) _Pragma("unroll") for (int n = 0; n < 2; ++n) _Pragma("unroll") for (int k = 0; k < 2; ++k) \
;         acc[ai][bj][m][n] = __builtin_amdgcn_mfma_f32_16x16x32_bf16(Bt[n][k], At[m][k], acc[ai][bj][m][n], 0, 0, 0); __builtin_amdgcn_s_setprio(0); } while (0)
; #define PG8_WAIT_V(n) asm volatile("s_waitcnt vmcnt(" #n ")" ::: "memory")
; #define PG8_WAIT_L(n) asm volatile("s_waitcnt lgkmcnt(" #n ")" ::: "memory")
; #define PG8_BAR __builtin_amdgcn_s_barrier()
; #define PG8_SCHED __builtin_amdgcn_sched_barrier(0)
; template <class Epi, class Sched>
; __device__ __forceinline__ void gemm_phase(LAS unsigned char* lds, const Gemm g, Sched S, const Epi& E) {
;     ...
;             PG8_WAIT_V(8); PG8_WAIT_L(0); PG8_BAR; PG8_MMA(1, 0, At, B0); PG8_MMA(1, 1, At, B1); PG8_BAR; PG8_SCHED;
;             PG8_LDB(B0, 1, 0); PG8_LDB(B1, 1, 1); PG8_SCHED; PG8_LDA(At, 1, 0); PG8_STAGE(PG8_SA(0, 1), a2 + hstepA, voffA);
;             PG8_WAIT_V(8); PG8_WAIT_L(0); PG8_BAR; PG8_MMA(0, 0, At, B0); PG8_MMA(0, 1, At, B1); PG8_BAR; PG8_SCHED;
	v_mfma_f32_16x16x32_bf16 v[6:9], v[150:153], v[216:219], v[6:9]
	v_mfma_f32_16x16x32_bf16 v[2:5], v[158:161], v[216:219], v[2:5]
	s_setprio 0
	s_add_i32 s65, 0, 0x18000
	s_add_i32 s99, 0, 0x1c000
	v_add_u32_e32 v142, s65, v180
	v_add_u32_e32 v158, s99, v180
	ds_read_b128 v[130:133], v142
	ds_read_b128 v[134:137], v142 offset:1024
	ds_read_b128 v[138:141], v142 offset:2048
	ds_read_b128 v[142:145], v142 offset:3072
	ds_read_b128 v[146:149], v158
	ds_read_b128 v[150:153], v158 offset:1024
	ds_read_b128 v[154:157], v158 offset:2048
	ds_read_b128 v[158:161], v158 offset:3072
	s_add_u32 s2, vcc_lo, 0x40000
	s_addc_u32 s3, vcc_hi, 0
	s_mov_b32 m0, s18
	ds_read_b128 v[174:177], v191 offset:32768
	ds_read_b128 v[192:195], v191 offset:33792
	ds_read_b128 v[196:199], v191 offset:34816
	ds_read_b128 v[200:203], v191 offset:35840
	ds_read_b128 v[204:207], v191 offset:36864
	ds_read_b128 v[208:211], v191 offset:37888
	ds_read_b128 v[212:215], v191 offset:38912
	ds_read_b128 v[216:219], v191 offset:39936
	global_load_lds_dwordx4 v164, s[2:3]
	s_mov_b32 m0, s19
	s_nop 0
	global_load_lds_dwordx4 v166, s[2:3]
	s_waitcnt vmcnt(8)
	s_waitcnt lgkmcnt(0)
	s_barrier
	s_setprio 1
	s_waitcnt lgkmcnt(0)
	v_mfma_f32_16x16x32_bf16 v[126:129], v[130:133], v[174:177], v[126:129]
	v_mfma_f32_16x16x32_bf16 v[122:125], v[138:141], v[174:177], v[122:125]
	v_mfma_f32_16x16x32_bf16 v[114:117], v[130:133], v[196:199], v[114:117]
	v_mfma_f32_16x16x32_bf16 v[106:109], v[138:141], v[196:199], v[106:109]
	v_mfma_f32_16x16x32_bf16 v[98:101], v[130:133], v[204:207], v[98:101]
	v_mfma_f32_16x16x32_bf16 v[90:93], v[138:141], v[204:207], v[90:93]
	v_mfma_f32_16x16x32_bf16 v[82:85], v[130:133], v[212:215], v[82:85]
	v_mfma_f32_16x16x32_bf16 v[74:77], v[138:141], v[212:215], v[74:77]
	v_mfma_f32_16x16x32_bf16 v[126:129], v[134:137], v[192:195], v[126:129]
	v_mfma_f32_16x16x32_bf16 v[122:125], v[142:145], v[192:195], v[122:125]
	v_mfma_f32_16x16x32_bf16 v[114:117], v[134:137], v[200:203], v[114:117]
	v_mfma_f32_16x16x32_bf16 v[106:109], v[142:145], v[200:203], v[106:109]
	v_mfma_f32_16x16x32_bf16 v[98:101], v[134:137], v[208:211], v[98:101]
	v_mfma_f32_16x16x32_bf16 v[90:93], v[142:145], v[208:211], v[90:93]
	v_mfma_f32_16x16x32_bf16 v[82:85], v[134:137], v[216:219], v[82:85]
	v_mfma_f32_16x16x32_bf16 v[74:77], v[142:145], v[216:219], v[74:77]
	s_setprio 0
	s_setprio 1
	v_mfma_f32_16x16x32_bf16 v[118:121], v[146:149], v[174:177], v[118:121]
	v_mfma_f32_16x16x32_bf16 v[110:113], v[154:157], v[174:177], v[110:113]
	v_mfma_f32_16x16x32_bf16 v[102:105], v[146:149], v[196:199], v[102:105]
	v_mfma_f32_16x16x32_bf16 v[94:97], v[154:157], v[196:199], v[94:97]
	v_mfma_f32_16x16x32_bf16 v[86:89], v[146:149], v[204:207], v[86:89]
	v_mfma_f32_16x16x32_bf16 v[78:81], v[154:157], v[204:207], v[78:81]
	v_mfma_f32_16x16x32_bf16 v[70:73], v[146:149], v[212:215], v[70:73]
	v_mfma_f32_16x16x32_bf16 v[66:69], v[154:157], v[212:215], v[66:69]
	v_mfma_f32_16x16x32_bf16 v[118:121], v[150:153], v[192:195], v[118:121]
	v_mfma_f32_16x16x32_bf16 v[110:113], v[158:161], v[192:195], v[110:113]
	v_mfma_f32_16x16x32_bf16 v[102:105], v[150:153], v[200:203], v[102:105]
	v_mfma_f32_16x16x32_bf16 v[94:97], v[158:161], v[200:203], v[94:97]
	v_mfma_f32_16x16x32_bf16 v[86:89], v[150:153], v[208:211], v[86:89]
	v_mfma_f32_16x16x32_bf16 v[78:81], v[158:161], v[208:211], v[78:81]
	s_setprio 2
	s_barrier
; #define PG8_STAGE(bufoff, gbase, voff) do { _Pragma("unroll") for (int _i = 0; _i < 2; ++_i) \
;         __builtin_amdgcn_global_load_lds((const unsigned*)((const char*)(gbase) + (voff)[_i]), (LAS unsigned*)(lds + (bufoff) + ldsw + _i * 8192), 16, 0, 0); } while (0)
; #define PG8_LDA(dst, b, h) do { _Pragma("unroll") for (int m = 0; m < 4; ++m) _Pragma("unroll") for (int k = 0; k < 2; ++k) dst[m][k] = *(const LAS bf16x8*)(lds + PG8_SA(b, h) + aoff + m * 2048 + k * 1024); } while (0)
; #define PG8_MMA(ai, bj, At, Bt) do { __builtin_amdgcn_s_setprio(1); _Pragma("unroll") for (int m = 0; m < 4; ++m) _Pragma("unroll") for (int n = 0; n < 2; ++n) _Pragma("unroll") for (int k = 0; k < 2; ++k) \
;         acc[ai][bj][m][n] = __builtin_amdgcn_mfma_f32_16x16x32_bf16(Bt[n][k], At[m][k], acc[ai][bj][m][n], 0, 0, 0); __builtin_amdgcn_s_setprio(0); } while (0)
; #define PG8_WAIT_V(n) asm volatile("s_waitcnt vmcnt(" #n ")" ::: "memory")
; #define PG8_WAIT_L(n) asm volatile("s_waitcnt lgkmcnt(" #n ")" ::: "memory")
; #define PG8_BAR __builtin_amdgcn_s_barrier()
; #define PG8_SCHED __builtin_amdgcn_sched_barrier(0)
; template <class Epi, class Sched>
; __device__ __forceinline__ void gemm_phase(LAS unsigned char* lds, const Gemm g, Sched S, const Epi& E) {
;     ...
;             PG8_WAIT_V(8); PG8_WAIT_L(0); PG8_BAR; PG8_MMA(0, 0, At, B0); PG8_MMA(0, 1, At, B1); PG8_BAR; PG8_SCHED;
;             PG8_LDA(At, 1, 1); PG8_STAGE(PG8_SB(1, 0), b3, voffB); PG8_STAGE(PG8_SB(1, 1), b3 + hstepB, voffB); PG8_STAGE(PG8_SA(1, 0), a3, voffA);
;             PG8_WAIT_V(8); PG8_WAIT_L(0); PG8_BAR; PG8_MMA(1, 0, At, B0); PG8_MMA(1, 1, At, B1); PG8_BAR; PG8_SCHED;
;         }
;         if (wr == 0) PG8_BAR;
;         if (Epi::NEEDS_RS && E.ssq && has_next) {
	v_mfma_f32_16x16x32_bf16 v[70:73], v[150:153], v[216:219], v[70:73]
	v_mfma_f32_16x16x32_bf16 v[66:69], v[158:161], v[216:219], v[66:69]
	s_setprio 0
	s_add_i32 s2, s65, s43
	s_add_u32 s100, s76, 0x80
	s_addc_u32 s101, s77, 0
	s_mov_b32 m0, s2
	ds_read_b128 v[174:177], v191 offset:49152
	ds_read_b128 v[192:195], v191 offset:50176
	ds_read_b128 v[196:199], v191 offset:51200
	ds_read_b128 v[200:203], v191 offset:52224
	ds_read_b128 v[204:207], v191 offset:53248
	ds_read_b128 v[208:211], v191 offset:54272
	ds_read_b128 v[212:215], v191 offset:55296
	ds_read_b128 v[216:219], v191 offset:56320
	global_load_lds_dwordx4 v0, s[100:101]
	s_add_i32 m0, s2, 0x2000
	s_add_u32 s2, s76, 0x40080
	s_addc_u32 s3, s77, 0
	s_add_i32 s65, s99, s43
	global_load_lds_dwordx4 v168, s[100:101]
	s_mov_b32 m0, s65
	s_nop 0
	global_load_lds_dwordx4 v0, s[2:3]
	s_add_i32 m0, s65, 0x2000
	s_nop 0
	global_load_lds_dwordx4 v168, s[2:3]
	s_add_u32 s100, vcc_lo, 0x80
	s_addc_u32 s101, vcc_hi, 0
	s_mov_b32 m0, s71
	s_nop 0
	global_load_lds_dwordx4 v164, s[100:101]
	s_mov_b32 m0, s40
	s_nop 0
	global_load_lds_dwordx4 v166, s[100:101]
	s_waitcnt vmcnt(8)
	s_waitcnt lgkmcnt(0)
	s_barrier
	s_setprio 1
	s_waitcnt lgkmcnt(0)
	v_mfma_f32_16x16x32_bf16 v[62:65], v[130:133], v[174:177], v[62:65]
	v_mfma_f32_16x16x32_bf16 v[58:61], v[138:141], v[174:177], v[58:61]
	v_mfma_f32_16x16x32_bf16 v[50:53], v[130:133], v[196:199], v[50:53]
	v_mfma_f32_16x16x32_bf16 v[42:45], v[138:141], v[196:199], v[42:45]
	v_mfma_f32_16x16x32_bf16 v[34:37], v[130:133], v[204:207], v[34:37]
	v_mfma_f32_16x16x32_bf16 v[26:29], v[138:141], v[204:207], v[26:29]
	v_mfma_f32_16x16x32_bf16 v[18:21], v[130:133], v[212:215], v[18:21]
	v_mfma_f32_16x16x32_bf16 v[10:13], v[138:141], v[212:215], v[10:13]
	v_mfma_f32_16x16x32_bf16 v[62:65], v[134:137], v[192:195], v[62:65]
	v_mfma_f32_16x16x32_bf16 v[58:61], v[142:145], v[192:195], v[58:61]
	v_mfma_f32_16x16x32_bf16 v[50:53], v[134:137], v[200:203], v[50:53]
	v_mfma_f32_16x16x32_bf16 v[42:45], v[142:145], v[200:203], v[42:45]
	v_mfma_f32_16x16x32_bf16 v[34:37], v[134:137], v[208:211], v[34:37]
	v_mfma_f32_16x16x32_bf16 v[26:29], v[142:145], v[208:211], v[26:29]
	v_mfma_f32_16x16x32_bf16 v[18:21], v[134:137], v[216:219], v[18:21]
	v_mfma_f32_16x16x32_bf16 v[10:13], v[142:145], v[216:219], v[10:13]
	s_setprio 0
	s_setprio 1
	v_mfma_f32_16x16x32_bf16 v[54:57], v[146:149], v[174:177], v[54:57]
	v_mfma_f32_16x16x32_bf16 v[46:49], v[154:157], v[174:177], v[46:49]
	v_mfma_f32_16x16x32_bf16 v[38:41], v[146:149], v[196:199], v[38:41]
	v_mfma_f32_16x16x32_bf16 v[30:33], v[154:157], v[196:199], v[30:33]
	v_mfma_f32_16x16x32_bf16 v[22:25], v[146:149], v[204:207], v[22:25]
	v_mfma_f32_16x16x32_bf16 v[14:17], v[154:157], v[204:207], v[14:17]
	v_mfma_f32_16x16x32_bf16 v[6:9], v[146:149], v[212:215], v[6:9]
	v_mfma_f32_16x16x32_bf16 v[2:5], v[154:157], v[212:215], v[2:5]
	v_mfma_f32_16x16x32_bf16 v[54:57], v[150:153], v[192:195], v[54:57]
	v_mfma_f32_16x16x32_bf16 v[46:49], v[158:161], v[192:195], v[46:49]
	v_mfma_f32_16x16x32_bf16 v[38:41], v[150:153], v[200:203], v[38:41]
	v_mfma_f32_16x16x32_bf16 v[30:33], v[158:161], v[200:203], v[30:33]
	v_mfma_f32_16x16x32_bf16 v[22:25], v[150:153], v[208:211], v[22:25]
	v_mfma_f32_16x16x32_bf16 v[14:17], v[158:161], v[208:211], v[14:17]
	s_setprio 2
	s_barrier
	v_mfma_f32_16x16x32_bf16 v[6:9], v[150:153], v[216:219], v[6:9]
	v_mfma_f32_16x16x32_bf16 v[2:5], v[158:161], v[216:219], v[2:5]
	s_setprio 0
	s_add_u32 s63, s63, 0x100
	s_addc_u32 s64, s64, 0
	s_add_u32 s0, s0, 0x100
	s_addc_u32 s1, s1, 0
	s_cmp_ge_u32 s67, s58
	s_mov_b32 s65, s67
	s_cbranch_scc0 .LBB0_630
	s_and_b64 vcc, exec, s[94:95]
	s_cbranch_vccz .LBB0_635
	s_barrier
	s_and_b64 s[0:1], s[96:97], s[10:11]
	s_andn2_b64 vcc, exec, s[0:1]
	s_mov_b64 s[0:1], -1
	s_cbranch_vccnz .LBB0_636

; #define PG8_STAGE(bufoff, gbase, voff) do { _Pragma("unroll") for (int _i = 0; _i < 2; ++_i) \
;         __builtin_amdgcn_global_load_lds((const unsigned*)((const char*)(gbase) + (voff)[_i]), (LAS unsigned*)(lds + (bufoff) + ldsw + _i * 8192), 16, 0, 0); } while (0)
; #define PG8_LDA(dst, b, h) do { _Pragma("unroll") for (int m = 0; m < 4; ++m) _Pragma("unroll") for (int k = 0; k < 2; ++k) dst[m][k] = *(const LAS bf16x8*)(lds + PG8_SA(b, h) + aoff + m * 2048 + k * 1024); } while (0)
; #define PG8_LDB(dst, b, h) do { _Pragma("unroll") for (int n = 0; n < 2; ++n) _Pragma("unroll") for (int k = 0; k < 2; ++k) dst[n][k] = *(const LAS bf16x8*)(lds + PG8_SB(b, h) + boff + n * 2048 + k * 1024); } while (0)
; #define PG8_MMA(ai, bj, At, Bt) do { __builtin_amdgcn_s_setprio(1); _Pragma("unroll") for (int m = 0; m < 4; ++m) _Pragma("unroll") for (int n = 0; n < 2; ++n) _Pragma("unroll") for (int k = 0; k < 2; ++k) \
;         acc[ai][bj][m][n] = __builtin_amdgcn_mfma_f32_16x16x32_bf16(Bt[n][k], At[m][k], acc[ai][bj][m][n], 0, 0, 0); __builtin_amdgcn_s_setprio(0); } while (0)
; #define PG8_WAIT_V(n) asm volatile("s_waitcnt vmcnt(" #n ")" ::: "memory")
; #define PG8_WAIT_L(n) asm volatile("s_waitcnt lgkmcnt(" #n ")" ::: "memory")
; #define PG8_BAR __builtin_amdgcn_s_barrier()
; #define PG8_SCHED __builtin_amdgcn_sched_barrier(0)
; template <class Epi, class Sched>
; __device__ __forceinline__ void gemm_phase(LAS unsigned char* lds, const Gemm g, Sched S, const Epi& E) {
;     ...
;         for (int t = 0; t < nt; t += 2) {
;             const bool last = (t == nt - 2);
;             const char* a1 = cA + (size_t)(t + 1) * kstep;
;             const char* a2 = last ? nA : cA + (size_t)(t + 2) * kstep; const char* b2 = last ? nB : cB + (size_t)(t + 2) * kstep;
;             const char* a3 = a2 + kstep; const char* b3 = b2 + kstep;
;             PG8_LDB(B0, 0, 0); PG8_LDB(B1, 0, 1); PG8_SCHED; PG8_LDA(At, 0, 0); PG8_STAGE(PG8_SA(1, 1), a1 + hstepA, voffA);
;             PG8_WAIT_V(8); PG8_WAIT_L(0); PG8_BAR; PG8_MMA(0, 0, At, B0); PG8_MMA(0, 1, At, B1); PG8_BAR; PG8_SCHED;
;             PG8_LDA(At, 0, 1); PG8_STAGE(PG8_SB(0, 0), b2, voffB); PG8_STAGE(PG8_SB(0, 1), b2 + hstepB, voffB); PG8_STAGE(PG8_SA(0, 0), a2, voffA);
;             PG8_WAIT_V(8); PG8_WAIT_L(0); PG8_BAR; PG8_MMA(1, 0, At, B0); PG8_MMA(1, 1, At, B1); PG8_BAR; PG8_SCHED;
.LBB0_727:
	s_add_i32 s21, s20, 2
	s_add_u32 s3, s42, 0x80
	s_addc_u32 s35, s43, 0
	s_add_i32 s52, 0, 0x10000
	s_cmp_eq_u32 s99, s20
	s_cselect_b32 s45, s89, s35
	s_cselect_b32 s44, s88, s3
	s_cselect_b32 s41, s91, s19
	s_cselect_b32 s40, s90, s11
	s_add_i32 s3, 0, 0x14000
	v_add_u32_e32 v126, s52, v192
	v_add_u32_e32 v170, s3, v192
	ds_read_b128 v[114:117], v126
	ds_read_b128 v[118:121], v126 offset:1024
	ds_read_b128 v[122:125], v126 offset:2048
	ds_read_b128 v[126:129], v126 offset:3072
	ds_read_b128 v[130:133], v170
	ds_read_b128 v[134:137], v170 offset:1024
	ds_read_b128 v[166:169], v170 offset:2048
	ds_read_b128 v[170:173], v170 offset:3072
	s_add_i32 m0, s85, 0xc000
	ds_read_b128 v[174:177], v194
	ds_read_b128 v[178:181], v194 offset:1024
	ds_read_b128 v[196:199], v194 offset:2048
	ds_read_b128 v[200:203], v194 offset:3072
	ds_read_b128 v[204:207], v194 offset:4096
	ds_read_b128 v[208:211], v194 offset:5120
	ds_read_b128 v[212:215], v194 offset:6144
	ds_read_b128 v[216:219], v194 offset:7168
	global_load_lds_dwordx4 v164, s[42:43]
	s_add_i32 m0, s85, 0xe000
	s_nop 0
	global_load_lds_dwordx4 v160, s[42:43]
	s_waitcnt vmcnt(8)
	s_waitcnt lgkmcnt(0)
	s_barrier
	s_setprio 1
	s_waitcnt lgkmcnt(0)
	v_mfma_f32_16x16x32_bf16 v[150:153], v[114:117], v[174:177], v[150:153]
	v_mfma_f32_16x16x32_bf16 v[146:149], v[122:125], v[174:177], v[146:149]
	v_mfma_f32_16x16x32_bf16 v[110:113], v[114:117], v[196:199], v[110:113]
	v_mfma_f32_16x16x32_bf16 v[106:109], v[122:125], v[196:199], v[106:109]
	v_mfma_f32_16x16x32_bf16 v[94:97], v[114:117], v[204:207], v[94:97]
	v_mfma_f32_16x16x32_bf16 v[90:93], v[122:125], v[204:207], v[90:93]
	v_mfma_f32_16x16x32_bf16 v[78:81], v[114:117], v[212:215], v[78:81]
	v_mfma_f32_16x16x32_bf16 v[74:77], v[122:125], v[212:215], v[74:77]
	v_mfma_f32_16x16x32_bf16 v[150:153], v[118:121], v[178:181], v[150:153]
	v_mfma_f32_16x16x32_bf16 v[146:149], v[126:129], v[178:181], v[146:149]
	v_mfma_f32_16x16x32_bf16 v[110:113], v[118:121], v[200:203], v[110:113]
	v_mfma_f32_16x16x32_bf16 v[106:109], v[126:129], v[200:203], v[106:109]
	v_mfma_f32_16x16x32_bf16 v[94:97], v[118:121], v[208:211], v[94:97]
	v_mfma_f32_16x16x32_bf16 v[90:93], v[126:129], v[208:211], v[90:93]
	v_mfma_f32_16x16x32_bf16 v[78:81], v[118:121], v[216:219], v[78:81]
	v_mfma_f32_16x16x32_bf16 v[74:77], v[126:129], v[216:219], v[74:77]
	s_setprio 0
	s_setprio 1
	v_mfma_f32_16x16x32_bf16 v[142:145], v[130:133], v[174:177], v[142:145]
	v_mfma_f32_16x16x32_bf16 v[138:141], v[166:169], v[174:177], v[138:141]
	v_mfma_f32_16x16x32_bf16 v[102:105], v[130:133], v[196:199], v[102:105]
	v_mfma_f32_16x16x32_bf16 v[98:101], v[166:169], v[196:199], v[98:101]
	v_mfma_f32_16x16x32_bf16 v[86:89], v[130:133], v[204:207], v[86:89]
	v_mfma_f32_16x16x32_bf16 v[82:85], v[166:169], v[204:207], v[82:85]
	v_mfma_f32_16x16x32_bf16 v[70:73], v[130:133], v[212:215], v[70:73]
	v_mfma_f32_16x16x32_bf16 v[66:69], v[166:169], v[212:215], v[66:69]
	v_mfma_f32_16x16x32_bf16 v[142:145], v[134:137], v[178:181], v[142:145]
	v_mfma_f32_16x16x32_bf16 v[138:141], v[170:173], v[178:181], v[138:141]
	v_mfma_f32_16x16x32_bf16 v[102:105], v[134:137], v[200:203], v[102:105]
	v_mfma_f32_16x16x32_bf16 v[98:101], v[170:173], v[200:203], v[98:101]
	v_mfma_f32_16x16x32_bf16 v[86:89], v[134:137], v[208:211], v[86:89]
	v_mfma_f32_16x16x32_bf16 v[82:85], v[170:173], v[208:211], v[82:85]
	s_setprio 2
	s_barrier
	v_mfma_f32_16x16x32_bf16 v[70:73], v[134:137], v[216:219], v[70:73]
	v_mfma_f32_16x16x32_bf16 v[66:69], v[170:173], v[216:219], v[66:69]
	s_setprio 0
	s_add_i32 s20, s52, s77
	s_add_u32 s100, s40, 0x80
	s_addc_u32 s101, s41, 0
	s_mov_b32 m0, s20
	ds_read_b128 v[174:177], v194 offset:16384
	ds_read_b128 v[178:181], v194 offset:17408
	ds_read_b128 v[196:199], v194 offset:18432
	ds_read_b128 v[200:203], v194 offset:19456
	ds_read_b128 v[204:207], v194 offset:20480
	ds_read_b128 v[208:211], v194 offset:21504
	ds_read_b128 v[212:215], v194 offset:22528
	ds_read_b128 v[216:219], v194 offset:23552
	global_load_lds_dwordx4 v0, s[40:41]
	s_add_i32 m0, s20, 0x2000
	s_add_i32 s3, s3, s77
	global_load_lds_dwordx4 v158, s[40:41]
	s_add_u32 s40, s40, s24
	s_addc_u32 s41, s41, s25
	s_mov_b32 m0, s3
	s_nop 0
	global_load_lds_dwordx4 v0, s[40:41]
	s_add_i32 m0, s3, 0x2000
	s_nop 0
	global_load_lds_dwordx4 v158, s[40:41]
	s_mov_b32 m0, s85
	s_nop 0
	global_load_lds_dwordx4 v154, s[44:45]
	s_mov_b32 m0, s92
	s_nop 0
	global_load_lds_dwordx4 v156, s[44:45]
	s_waitcnt vmcnt(8)
	s_waitcnt lgkmcnt(0)
	s_barrier
	s_setprio 1
	s_waitcnt lgkmcnt(0)
	v_mfma_f32_16x16x32_bf16 v[62:65], v[114:117], v[174:177], v[62:65]
	v_mfma_f32_16x16x32_bf16 v[58:61], v[122:125], v[174:177], v[58:61]
	v_mfma_f32_16x16x32_bf16 v[46:49], v[114:117], v[196:199], v[46:49]
	v_mfma_f32_16x16x32_bf16 v[42:45], v[122:125], v[196:199], v[42:45]
	v_mfma_f32_16x16x32_bf16 v[30:33], v[114:117], v[204:207], v[30:33]
	v_mfma_f32_16x16x32_bf16 v[26:29], v[122:125], v[204:207], v[26:29]
	v_mfma_f32_16x16x32_bf16 v[14:17], v[114:117], v[212:215], v[14:17]
	v_mfma_f32_16x16x32_bf16 v[10:13], v[122:125], v[212:215], v[10:13]
	v_mfma_f32_16x16x32_bf16 v[62:65], v[118:121], v[178:181], v[62:65]
	v_mfma_f32_16x16x32_bf16 v[58:61], v[126:129], v[178:181], v[58:61]
	v_mfma_f32_16x16x32_bf16 v[46:49], v[118:121], v[200:203], v[46:49]
	v_mfma_f32_16x16x32_bf16 v[42:45], v[126:129], v[200:203], v[42:45]
	v_mfma_f32_16x16x32_bf16 v[30:33], v[118:121], v[208:211], v[30:33]
	v_mfma_f32_16x16x32_bf16 v[26:29], v[126:129], v[208:211], v[26:29]
	v_mfma_f32_16x16x32_bf16 v[14:17], v[118:121], v[216:219], v[14:17]
	v_mfma_f32_16x16x32_bf16 v[10:13], v[126:129], v[216:219], v[10:13]
	s_setprio 0
	s_setprio 1
	v_mfma_f32_16x16x32_bf16 v[54:57], v[130:133], v[174:177], v[54:57]
	v_mfma_f32_16x16x32_bf16 v[50:53], v[166:169], v[174:177], v[50:53]
	v_mfma_f32_16x16x32_bf16 v[38:41], v[130:133], v[196:199], v[38:41]
	v_mfma_f32_16x16x32_bf16 v[34:37], v[166:169], v[196:199], v[34:37]
	v_mfma_f32_16x16x32_bf16 v[22:25], v[130:133], v[204:207], v[22:25]
	v_mfma_f32_16x16x32_bf16 v[18:21], v[166:169], v[204:207], v[18:21]
	v_mfma_f32_16x16x32_bf16 v[6:9], v[130:133], v[212:215], v[6:9]
	v_mfma_f32_16x16x32_bf16 v[2:5], v[166:169], v[212:215], v[2:5]
	v_mfma_f32_16x16x32_bf16 v[54:57], v[134:137], v[178:181], v[54:57]
	v_mfma_f32_16x16x32_bf16 v[50:53], v[170:173], v[178:181], v[50:53]
	v_mfma_f32_16x16x32_bf16 v[38:41], v[134:137], v[200:203], v[38:41]
	v_mfma_f32_16x16x32_bf16 v[34:37], v[170:173], v[200:203], v[34:37]
	v_mfma_f32_16x16x32_bf16 v[22:25], v[134:137], v[208:211], v[22:25]
	v_mfma_f32_16x16x32_bf16 v[18:21], v[170:173], v[208:211], v[18:21]
	s_setprio 2
	s_barrier
; #define PG8_STAGE(bufoff, gbase, voff) do { _Pragma("unroll") for (int _i = 0; _i < 2; ++_i) \
;         __builtin_amdgcn_global_load_lds((const unsigned*)((const char*)(gbase) + (voff)[_i]), (LAS unsigned*)(lds + (bufoff) + ldsw + _i * 8192), 16, 0, 0); } while (0)
; #define PG8_LDA(dst, b, h) do { _Pragma("unroll") for (int m = 0; m < 4; ++m) _Pragma("unroll") for (int k = 0; k < 2; ++k) dst[m][k] = *(const LAS bf16x8*)(lds + PG8_SA(b, h) + aoff + m * 2048 + k * 1024); } while (0)
; #define PG8_LDB(dst, b, h) do { _Pragma("unroll") for (int n = 0; n < 2; ++n) _Pragma("unroll") for (int k = 0; k < 2; ++k) dst[n][k] = *(const LAS bf16x8*)(lds + PG8_SB(b, h) + boff + n * 2048 + k * 1024); } while (0)
; #define PG8_MMA(ai, bj, At, Bt) do { __builtin_amdgcn_s_setprio(1); _Pragma("unroll") for (int m = 0; m < 4; ++m) _Pragma("unroll") for (int n = 0; n < 2; ++n) _Pragma("unroll") for (int k = 0; k < 2; ++k) \
;         acc[ai][bj][m][n] = __builtin_amdgcn_mfma_f32_16x16x32_bf16(Bt[n][k], At[m][k], acc[ai][bj][m][n], 0, 0, 0); __builtin_amdgcn_s_setprio(0); } while (0)
; #define PG8_WAIT_V(n) asm volatile("s_waitcnt vmcnt(" #n ")" ::: "memory")
; #define PG8_WAIT_L(n) asm volatile("s_waitcnt lgkmcnt(" #n ")" ::: "memory")
; #define PG8_BAR __builtin_amdgcn_s_barrier()
; #define PG8_SCHED __builtin_amdgcn_sched_barrier(0)
; template <class Epi, class Sched>
; __device__ __forceinline__ void gemm_phase(LAS unsigned char* lds, const Gemm g, Sched S, const Epi& E) {
;     ...
;             PG8_WAIT_V(8); PG8_WAIT_L(0); PG8_BAR; PG8_MMA(1, 0, At, B0); PG8_MMA(1, 1, At, B1); PG8_BAR; PG8_SCHED;
;             PG8_LDB(B0, 1, 0); PG8_LDB(B1, 1, 1); PG8_SCHED; PG8_LDA(At, 1, 0); PG8_STAGE(PG8_SA(0, 1), a2 + hstepA, voffA);
;             PG8_WAIT_V(8); PG8_WAIT_L(0); PG8_BAR; PG8_MMA(0, 0, At, B0); PG8_MMA(0, 1, At, B1); PG8_BAR; PG8_SCHED;
;             PG8_LDA(At, 1, 1); PG8_STAGE(PG8_SB(1, 0), b3, voffB); PG8_STAGE(PG8_SB(1, 1), b3 + hstepB, voffB); PG8_STAGE(PG8_SA(1, 0), a3, voffA);
;             PG8_WAIT_V(8); PG8_WAIT_L(0); PG8_BAR; PG8_MMA(1, 0, At, B0); PG8_MMA(1, 1, At, B1); PG8_BAR; PG8_SCHED;
;         }
;         if (wr == 0) PG8_BAR;
;         if (Epi::NEEDS_RS && E.ssq && has_next) {
	v_mfma_f32_16x16x32_bf16 v[6:9], v[134:137], v[216:219], v[6:9]
	v_mfma_f32_16x16x32_bf16 v[2:5], v[170:173], v[216:219], v[2:5]
	s_setprio 0
	s_add_i32 s3, 0, 0x18000
	s_add_i32 s20, 0, 0x1c000
	v_add_u32_e32 v126, s3, v192
	v_add_u32_e32 v170, s20, v192
	ds_read_b128 v[114:117], v126
	ds_read_b128 v[118:121], v126 offset:1024
	ds_read_b128 v[122:125], v126 offset:2048
	ds_read_b128 v[126:129], v126 offset:3072
	ds_read_b128 v[130:133], v170
	ds_read_b128 v[134:137], v170 offset:1024
	ds_read_b128 v[166:169], v170 offset:2048
	ds_read_b128 v[170:173], v170 offset:3072
	s_add_u32 s40, s44, s8
	s_addc_u32 s41, s45, 0
	s_mov_b32 m0, s93
	ds_read_b128 v[174:177], v194 offset:32768
	ds_read_b128 v[178:181], v194 offset:33792
	ds_read_b128 v[196:199], v194 offset:34816
	ds_read_b128 v[200:203], v194 offset:35840
	ds_read_b128 v[204:207], v194 offset:36864
	ds_read_b128 v[208:211], v194 offset:37888
	ds_read_b128 v[212:215], v194 offset:38912
	ds_read_b128 v[216:219], v194 offset:39936
	global_load_lds_dwordx4 v154, s[40:41]
	s_mov_b32 m0, s94
	s_nop 0
	global_load_lds_dwordx4 v156, s[40:41]
	s_waitcnt vmcnt(8)
	s_waitcnt lgkmcnt(0)
	s_barrier
	s_setprio 1
	s_waitcnt lgkmcnt(0)
	v_mfma_f32_16x16x32_bf16 v[150:153], v[114:117], v[174:177], v[150:153]
	v_mfma_f32_16x16x32_bf16 v[146:149], v[122:125], v[174:177], v[146:149]
	v_mfma_f32_16x16x32_bf16 v[110:113], v[114:117], v[196:199], v[110:113]
	v_mfma_f32_16x16x32_bf16 v[106:109], v[122:125], v[196:199], v[106:109]
	v_mfma_f32_16x16x32_bf16 v[94:97], v[114:117], v[204:207], v[94:97]
	v_mfma_f32_16x16x32_bf16 v[90:93], v[122:125], v[204:207], v[90:93]
	v_mfma_f32_16x16x32_bf16 v[78:81], v[114:117], v[212:215], v[78:81]
	v_mfma_f32_16x16x32_bf16 v[74:77], v[122:125], v[212:215], v[74:77]
	v_mfma_f32_16x16x32_bf16 v[150:153], v[118:121], v[178:181], v[150:153]
	v_mfma_f32_16x16x32_bf16 v[146:149], v[126:129], v[178:181], v[146:149]
	v_mfma_f32_16x16x32_bf16 v[110:113], v[118:121], v[200:203], v[110:113]
	v_mfma_f32_16x16x32_bf16 v[106:109], v[126:129], v[200:203], v[106:109]
	v_mfma_f32_16x16x32_bf16 v[94:97], v[118:121], v[208:211], v[94:97]
	v_mfma_f32_16x16x32_bf16 v[90:93], v[126:129], v[208:211], v[90:93]
	v_mfma_f32_16x16x32_bf16 v[78:81], v[118:121], v[216:219], v[78:81]
	v_mfma_f32_16x16x32_bf16 v[74:77], v[126:129], v[216:219], v[74:77]
	s_setprio 0
	s_setprio 1
	v_mfma_f32_16x16x32_bf16 v[142:145], v[130:133], v[174:177], v[142:145]
	v_mfma_f32_16x16x32_bf16 v[138:141], v[166:169], v[174:177], v[138:141]
	v_mfma_f32_16x16x32_bf16 v[102:105], v[130:133], v[196:199], v[102:105]
	v_mfma_f32_16x16x32_bf16 v[98:101], v[166:169], v[196:199], v[98:101]
	v_mfma_f32_16x16x32_bf16 v[86:89], v[130:133], v[204:207], v[86:89]
	v_mfma_f32_16x16x32_bf16 v[82:85], v[166:169], v[204:207], v[82:85]
	v_mfma_f32_16x16x32_bf16 v[70:73], v[130:133], v[212:215], v[70:73]
	v_mfma_f32_16x16x32_bf16 v[66:69], v[166:169], v[212:215], v[66:69]
	v_mfma_f32_16x16x32_bf16 v[142:145], v[134:137], v[178:181], v[142:145]
	v_mfma_f32_16x16x32_bf16 v[138:141], v[170:173], v[178:181], v[138:141]
	v_mfma_f32_16x16x32_bf16 v[102:105], v[134:137], v[200:203], v[102:105]
	v_mfma_f32_16x16x32_bf16 v[98:101], v[170:173], v[200:203], v[98:101]
	v_mfma_f32_16x16x32_bf16 v[86:89], v[134:137], v[208:211], v[86:89]
	v_mfma_f32_16x16x32_bf16 v[82:85], v[170:173], v[208:211], v[82:85]
	s_setprio 2
	s_barrier
	v_mfma_f32_16x16x32_bf16 v[70:73], v[134:137], v[216:219], v[70:73]
	v_mfma_f32_16x16x32_bf16 v[66:69], v[170:173], v[216:219], v[66:69]
	s_setprio 0
	s_add_i32 s3, s3, s77
	s_mov_b32 m0, s3
	ds_read_b128 v[174:177], v194 offset:49152
	ds_read_b128 v[178:181], v194 offset:50176
	ds_read_b128 v[196:199], v194 offset:51200
	ds_read_b128 v[200:203], v194 offset:52224
	ds_read_b128 v[204:207], v194 offset:53248
	ds_read_b128 v[208:211], v194 offset:54272
	ds_read_b128 v[212:215], v194 offset:55296
	ds_read_b128 v[216:219], v194 offset:56320
	global_load_lds_dwordx4 v0, s[100:101]
	s_add_i32 m0, s3, 0x2000
	s_add_i32 s3, s20, s77
	global_load_lds_dwordx4 v158, s[100:101]
	s_add_u32 s100, s100, s24
	s_addc_u32 s101, s101, s25
	s_mov_b32 m0, s3
	s_nop 0
	global_load_lds_dwordx4 v0, s[100:101]
	s_add_i32 m0, s3, 0x2000
	s_nop 0
	global_load_lds_dwordx4 v158, s[100:101]
	s_add_u32 s100, s44, 0x80
	s_addc_u32 s101, s45, 0
	s_mov_b32 m0, s97
	s_nop 0
	global_load_lds_dwordx4 v154, s[100:101]
	s_mov_b32 m0, s98
	s_nop 0
	global_load_lds_dwordx4 v156, s[100:101]
	s_waitcnt vmcnt(8)
	s_waitcnt lgkmcnt(0)
	s_barrier
	s_setprio 1
	s_waitcnt lgkmcnt(0)
	v_mfma_f32_16x16x32_bf16 v[62:65], v[114:117], v[174:177], v[62:65]
	v_mfma_f32_16x16x32_bf16 v[58:61], v[122:125], v[174:177], v[58:61]
	v_mfma_f32_16x16x32_bf16 v[46:49], v[114:117], v[196:199], v[46:49]
	v_mfma_f32_16x16x32_bf16 v[42:45], v[122:125], v[196:199], v[42:45]
	v_mfma_f32_16x16x32_bf16 v[30:33], v[114:117], v[204:207], v[30:33]
	v_mfma_f32_16x16x32_bf16 v[26:29], v[122:125], v[204:207], v[26:29]
	v_mfma_f32_16x16x32_bf16 v[14:17], v[114:117], v[212:215], v[14:17]
	v_mfma_f32_16x16x32_bf16 v[10:13], v[122:125], v[212:215], v[10:13]
	v_mfma_f32_16x16x32_bf16 v[62:65], v[118:121], v[178:181], v[62:65]
	v_mfma_f32_16x16x32_bf16 v[58:61], v[126:129], v[178:181], v[58:61]
	v_mfma_f32_16x16x32_bf16 v[46:49], v[118:121], v[200:203], v[46:49]
	v_mfma_f32_16x16x32_bf16 v[42:45], v[126:129], v[200:203], v[42:45]
	v_mfma_f32_16x16x32_bf16 v[30:33], v[118:121], v[208:211], v[30:33]
	v_mfma_f32_16x16x32_bf16 v[26:29], v[126:129], v[208:211], v[26:29]
	v_mfma_f32_16x16x32_bf16 v[14:17], v[118:121], v[216:219], v[14:17]
	v_mfma_f32_16x16x32_bf16 v[10:13], v[126:129], v[216:219], v[10:13]
	s_setprio 0
	s_setprio 1
	v_mfma_f32_16x16x32_bf16 v[54:57], v[130:133], v[174:177], v[54:57]
	v_mfma_f32_16x16x32_bf16 v[50:53], v[166:169], v[174:177], v[50:53]
	v_mfma_f32_16x16x32_bf16 v[38:41], v[130:133], v[196:199], v[38:41]
	v_mfma_f32_16x16x32_bf16 v[34:37], v[166:169], v[196:199], v[34:37]
	v_mfma_f32_16x16x32_bf16 v[22:25], v[130:133], v[204:207], v[22:25]
	v_mfma_f32_16x16x32_bf16 v[18:21], v[166:169], v[204:207], v[18:21]
	v_mfma_f32_16x16x32_bf16 v[6:9], v[130:133], v[212:215], v[6:9]
	v_mfma_f32_16x16x32_bf16 v[2:5], v[166:169], v[212:215], v[2:5]
	v_mfma_f32_16x16x32_bf16 v[54:57], v[134:137], v[178:181], v[54:57]
	v_mfma_f32_16x16x32_bf16 v[50:53], v[170:173], v[178:181], v[50:53]
	v_mfma_f32_16x16x32_bf16 v[38:41], v[134:137], v[200:203], v[38:41]
	v_mfma_f32_16x16x32_bf16 v[34:37], v[170:173], v[200:203], v[34:37]
	v_mfma_f32_16x16x32_bf16 v[22:25], v[134:137], v[208:211], v[22:25]
	v_mfma_f32_16x16x32_bf16 v[18:21], v[170:173], v[208:211], v[18:21]
	s_setprio 2
	s_barrier
	v_mfma_f32_16x16x32_bf16 v[6:9], v[134:137], v[216:219], v[6:9]
	v_mfma_f32_16x16x32_bf16 v[2:5], v[170:173], v[216:219], v[2:5]
	s_setprio 0
	s_add_u32 s11, s11, 0x100
	s_addc_u32 s19, s19, 0
	s_add_u32 s42, s42, 0x100
	s_addc_u32 s43, s43, 0
	s_cmp_ge_u32 s21, s96
	s_mov_b32 s20, s21
	s_cbranch_scc0 .LBB0_727
	s_and_b64 vcc, exec, s[30:31]
	s_cbranch_vccz .LBB0_730
	s_barrier

; #define PG8_STAGE(bufoff, gbase, voff) do { _Pragma("unroll") for (int _i = 0; _i < 2; ++_i) \
;         __builtin_amdgcn_global_load_lds((const unsigned*)((const char*)(gbase) + (voff)[_i]), (LAS unsigned*)(lds + (bufoff) + ldsw + _i * 8192), 16, 0, 0); } while (0)
; #define PG8_LDA(dst, b, h) do { _Pragma("unroll") for (int m = 0; m < 4; ++m) _Pragma("unroll") for (int k = 0; k < 2; ++k) dst[m][k] = *(const LAS bf16x8*)(lds + PG8_SA(b, h) + aoff + m * 2048 + k * 1024); } while (0)
; #define PG8_LDB(dst, b, h) do { _Pragma("unroll") for (int n = 0; n < 2; ++n) _Pragma("unroll") for (int k = 0; k < 2; ++k) dst[n][k] = *(const LAS bf16x8*)(lds + PG8_SB(b, h) + boff + n * 2048 + k * 1024); } while (0)
; #define PG8_MMA(ai, bj, At, Bt) do { __builtin_amdgcn_s_setprio(1); _Pragma("unroll") for (int m = 0; m < 4; ++m) _Pragma("unroll") for (int n = 0; n < 2; ++n) _Pragma("unroll") for (int k = 0; k < 2; ++k) \
;         acc[ai][bj][m][n] = __builtin_amdgcn_mfma_f32_16x16x32_bf16(Bt[n][k], At[m][k], acc[ai][bj][m][n], 0, 0, 0); __builtin_amdgcn_s_setprio(0); } while (0)
; #define PG8_WAIT_V(n) asm volatile("s_waitcnt vmcnt(" #n ")" ::: "memory")
; #define PG8_WAIT_L(n) asm volatile("s_waitcnt lgkmcnt(" #n ")" ::: "memory")
; #define PG8_BAR __builtin_amdgcn_s_barrier()
; #define PG8_SCHED __builtin_amdgcn_sched_barrier(0)
; template <class Epi, class Sched>
; __device__ __forceinline__ void gemm_phase(LAS unsigned char* lds, const Gemm g, Sched S, const Epi& E) {
;     ...
;         for (int t = 0; t < nt; t += 2) {
;             const bool last = (t == nt - 2);
;             const char* a1 = cA + (size_t)(t + 1) * kstep;
;             const char* a2 = last ? nA : cA + (size_t)(t + 2) * kstep; const char* b2 = last ? nB : cB + (size_t)(t + 2) * kstep;
;             const char* a3 = a2 + kstep; const char* b3 = b2 + kstep;
;             PG8_LDB(B0, 0, 0); PG8_LDB(B1, 0, 1); PG8_SCHED; PG8_LDA(At, 0, 0); PG8_STAGE(PG8_SA(1, 1), a1 + hstepA, voffA);
;             PG8_WAIT_V(8); PG8_WAIT_L(0); PG8_BAR; PG8_MMA(0, 0, At, B0); PG8_MMA(0, 1, At, B1); PG8_BAR; PG8_SCHED;
;             PG8_LDA(At, 0, 1); PG8_STAGE(PG8_SB(0, 0), b2, voffB); PG8_STAGE(PG8_SB(0, 1), b2 + hstepB, voffB); PG8_STAGE(PG8_SA(0, 0), a2, voffA);
;             PG8_WAIT_V(8); PG8_WAIT_L(0); PG8_BAR; PG8_MMA(1, 0, At, B0); PG8_MMA(1, 1, At, B1); PG8_BAR; PG8_SCHED;
.LBB0_770:
	s_add_u32 s3, s10, 0xfffc0080
	s_addc_u32 s42, s11, -1
	s_add_i32 s71, 0, 0x10000
	s_cmp_eq_u32 s70, 12
	s_cselect_b32 s45, s60, s42
	s_cselect_b32 s44, s61, s3
	s_cselect_b32 s43, s62, s65
	s_cselect_b32 s42, s63, s64
	s_add_i32 s3, 0, 0x14000
	v_add_u32_e32 v142, s71, v183
	v_add_u32_e32 v158, s3, v183
	ds_read_b128 v[130:133], v142
	ds_read_b128 v[134:137], v142 offset:1024
	ds_read_b128 v[138:141], v142 offset:2048
	ds_read_b128 v[142:145], v142 offset:3072
	ds_read_b128 v[146:149], v158
	ds_read_b128 v[150:153], v158 offset:1024
	ds_read_b128 v[154:157], v158 offset:2048
	ds_read_b128 v[158:161], v158 offset:3072
	s_add_i32 m0, s9, 0xc000
	ds_read_b128 v[174:177], v194
	ds_read_b128 v[196:199], v194 offset:1024
	ds_read_b128 v[200:203], v194 offset:2048
	ds_read_b128 v[204:207], v194 offset:3072
	ds_read_b128 v[208:211], v194 offset:4096
	ds_read_b128 v[212:215], v194 offset:5120
	ds_read_b128 v[216:219], v194 offset:6144
	ds_read_b128 v[220:223], v194 offset:7168
	global_load_lds_dwordx4 v172, s[10:11]
	s_add_i32 m0, s9, 0xe000
	s_nop 0
	global_load_lds_dwordx4 v170, s[10:11]
	s_waitcnt vmcnt(8)
	s_waitcnt lgkmcnt(0)
	s_barrier
	s_setprio 1
	s_waitcnt lgkmcnt(0)
	v_mfma_f32_16x16x32_bf16 v[126:129], v[130:133], v[174:177], v[126:129]
	v_mfma_f32_16x16x32_bf16 v[118:121], v[138:141], v[174:177], v[118:121]
	v_mfma_f32_16x16x32_bf16 v[110:113], v[130:133], v[200:203], v[110:113]
	v_mfma_f32_16x16x32_bf16 v[102:105], v[138:141], v[200:203], v[102:105]
	v_mfma_f32_16x16x32_bf16 v[94:97], v[130:133], v[208:211], v[94:97]
	v_mfma_f32_16x16x32_bf16 v[86:89], v[138:141], v[208:211], v[86:89]
	v_mfma_f32_16x16x32_bf16 v[78:81], v[130:133], v[216:219], v[78:81]
	v_mfma_f32_16x16x32_bf16 v[70:73], v[138:141], v[216:219], v[70:73]
	v_mfma_f32_16x16x32_bf16 v[126:129], v[134:137], v[196:199], v[126:129]
	v_mfma_f32_16x16x32_bf16 v[118:121], v[142:145], v[196:199], v[118:121]
	v_mfma_f32_16x16x32_bf16 v[110:113], v[134:137], v[204:207], v[110:113]
	v_mfma_f32_16x16x32_bf16 v[102:105], v[142:145], v[204:207], v[102:105]
	v_mfma_f32_16x16x32_bf16 v[94:97], v[134:137], v[212:215], v[94:97]
	v_mfma_f32_16x16x32_bf16 v[86:89], v[142:145], v[212:215], v[86:89]
	v_mfma_f32_16x16x32_bf16 v[78:81], v[134:137], v[220:223], v[78:81]
	v_mfma_f32_16x16x32_bf16 v[70:73], v[142:145], v[220:223], v[70:73]
	s_setprio 0
	s_setprio 1
	v_mfma_f32_16x16x32_bf16 v[122:125], v[146:149], v[174:177], v[122:125]
	v_mfma_f32_16x16x32_bf16 v[114:117], v[154:157], v[174:177], v[114:117]
	v_mfma_f32_16x16x32_bf16 v[106:109], v[146:149], v[200:203], v[106:109]
	v_mfma_f32_16x16x32_bf16 v[98:101], v[154:157], v[200:203], v[98:101]
	v_mfma_f32_16x16x32_bf16 v[90:93], v[146:149], v[208:211], v[90:93]
	v_mfma_f32_16x16x32_bf16 v[82:85], v[154:157], v[208:211], v[82:85]
	v_mfma_f32_16x16x32_bf16 v[74:77], v[146:149], v[216:219], v[74:77]
	v_mfma_f32_16x16x32_bf16 v[66:69], v[154:157], v[216:219], v[66:69]
	v_mfma_f32_16x16x32_bf16 v[122:125], v[150:153], v[196:199], v[122:125]
	v_mfma_f32_16x16x32_bf16 v[114:117], v[158:161], v[196:199], v[114:117]
	v_mfma_f32_16x16x32_bf16 v[106:109], v[150:153], v[204:207], v[106:109]
	v_mfma_f32_16x16x32_bf16 v[98:101], v[158:161], v[204:207], v[98:101]
	v_mfma_f32_16x16x32_bf16 v[90:93], v[150:153], v[212:215], v[90:93]
	v_mfma_f32_16x16x32_bf16 v[82:85], v[158:161], v[212:215], v[82:85]
	s_setprio 2
	s_barrier
	v_mfma_f32_16x16x32_bf16 v[74:77], v[150:153], v[220:223], v[74:77]
	v_mfma_f32_16x16x32_bf16 v[66:69], v[158:161], v[220:223], v[66:69]
	s_setprio 0
	s_add_i32 s71, s71, s7
	s_mov_b32 m0, s71
	ds_read_b128 v[174:177], v194 offset:16384
	ds_read_b128 v[196:199], v194 offset:17408
	ds_read_b128 v[200:203], v194 offset:18432
	ds_read_b128 v[204:207], v194 offset:19456
	ds_read_b128 v[208:211], v194 offset:20480
	ds_read_b128 v[212:215], v194 offset:21504
	ds_read_b128 v[216:219], v194 offset:22528
	ds_read_b128 v[220:223], v194 offset:23552
	global_load_lds_dwordx4 v0, s[42:43]
	s_add_i32 m0, s71, 0x2000
	s_add_u32 s96, s42, 0x40000
	s_addc_u32 s97, s43, 0
	s_add_i32 s3, s3, s7
	global_load_lds_dwordx4 v164, s[42:43]
	s_mov_b32 m0, s3
	s_nop 0
	global_load_lds_dwordx4 v0, s[96:97]
	s_add_i32 m0, s3, 0x2000
	s_nop 0
	global_load_lds_dwordx4 v164, s[96:97]
	s_mov_b32 m0, s9
	s_nop 0
	global_load_lds_dwordx4 v168, s[44:45]
	s_mov_b32 m0, s56
	s_nop 0
	global_load_lds_dwordx4 v166, s[44:45]
	s_waitcnt vmcnt(8)
	s_waitcnt lgkmcnt(0)
	s_barrier
	s_setprio 1
	s_waitcnt lgkmcnt(0)
	v_mfma_f32_16x16x32_bf16 v[62:65], v[130:133], v[174:177], v[62:65]
	v_mfma_f32_16x16x32_bf16 v[54:57], v[138:141], v[174:177], v[54:57]
	v_mfma_f32_16x16x32_bf16 v[46:49], v[130:133], v[200:203], v[46:49]
	v_mfma_f32_16x16x32_bf16 v[38:41], v[138:141], v[200:203], v[38:41]
	v_mfma_f32_16x16x32_bf16 v[30:33], v[130:133], v[208:211], v[30:33]
	v_mfma_f32_16x16x32_bf16 v[22:25], v[138:141], v[208:211], v[22:25]
	v_mfma_f32_16x16x32_bf16 v[14:17], v[130:133], v[216:219], v[14:17]
	v_mfma_f32_16x16x32_bf16 v[6:9], v[138:141], v[216:219], v[6:9]
	v_mfma_f32_16x16x32_bf16 v[62:65], v[134:137], v[196:199], v[62:65]
	v_mfma_f32_16x16x32_bf16 v[54:57], v[142:145], v[196:199], v[54:57]
	v_mfma_f32_16x16x32_bf16 v[46:49], v[134:137], v[204:207], v[46:49]
	v_mfma_f32_16x16x32_bf16 v[38:41], v[142:145], v[204:207], v[38:41]
	v_mfma_f32_16x16x32_bf16 v[30:33], v[134:137], v[212:215], v[30:33]
	v_mfma_f32_16x16x32_bf16 v[22:25], v[142:145], v[212:215], v[22:25]
	v_mfma_f32_16x16x32_bf16 v[14:17], v[134:137], v[220:223], v[14:17]
	v_mfma_f32_16x16x32_bf16 v[6:9], v[142:145], v[220:223], v[6:9]
	s_setprio 0
	s_setprio 1
	v_mfma_f32_16x16x32_bf16 v[58:61], v[146:149], v[174:177], v[58:61]
	v_mfma_f32_16x16x32_bf16 v[50:53], v[154:157], v[174:177], v[50:53]
	v_mfma_f32_16x16x32_bf16 v[42:45], v[146:149], v[200:203], v[42:45]
	v_mfma_f32_16x16x32_bf16 v[34:37], v[154:157], v[200:203], v[34:37]
	v_mfma_f32_16x16x32_bf16 v[26:29], v[146:149], v[208:211], v[26:29]
	v_mfma_f32_16x16x32_bf16 v[18:21], v[154:157], v[208:211], v[18:21]
	v_mfma_f32_16x16x32_bf16 v[10:13], v[146:149], v[216:219], v[10:13]
	v_mfma_f32_16x16x32_bf16 v[2:5], v[154:157], v[216:219], v[2:5]
	v_mfma_f32_16x16x32_bf16 v[58:61], v[150:153], v[196:199], v[58:61]
	v_mfma_f32_16x16x32_bf16 v[50:53], v[158:161], v[196:199], v[50:53]
	v_mfma_f32_16x16x32_bf16 v[42:45], v[150:153], v[204:207], v[42:45]
	v_mfma_f32_16x16x32_bf16 v[34:37], v[158:161], v[204:207], v[34:37]
	v_mfma_f32_16x16x32_bf16 v[26:29], v[150:153], v[212:215], v[26:29]
	v_mfma_f32_16x16x32_bf16 v[18:21], v[158:161], v[212:215], v[18:21]
	s_setprio 2
	s_barrier
; #define PG8_STAGE(bufoff, gbase, voff) do { _Pragma("unroll") for (int _i = 0; _i < 2; ++_i) \
;         __builtin_amdgcn_global_load_lds((const unsigned*)((const char*)(gbase) + (voff)[_i]), (LAS unsigned*)(lds + (bufoff) + ldsw + _i * 8192), 16, 0, 0); } while (0)
; #define PG8_LDA(dst, b, h) do { _Pragma("unroll") for (int m = 0; m < 4; ++m) _Pragma("unroll") for (int k = 0; k < 2; ++k) dst[m][k] = *(const LAS bf16x8*)(lds + PG8_SA(b, h) + aoff + m * 2048 + k * 1024); } while (0)
; #define PG8_LDB(dst, b, h) do { _Pragma("unroll") for (int n = 0; n < 2; ++n) _Pragma("unroll") for (int k = 0; k < 2; ++k) dst[n][k] = *(const LAS bf16x8*)(lds + PG8_SB(b, h) + boff + n * 2048 + k * 1024); } while (0)
; #define PG8_MMA(ai, bj, At, Bt) do { __builtin_amdgcn_s_setprio(1); _Pragma("unroll") for (int m = 0; m < 4; ++m) _Pragma("unroll") for (int n = 0; n < 2; ++n) _Pragma("unroll") for (int k = 0; k < 2; ++k) \
;         acc[ai][bj][m][n] = __builtin_amdgcn_mfma_f32_16x16x32_bf16(Bt[n][k], At[m][k], acc[ai][bj][m][n], 0, 0, 0); __builtin_amdgcn_s_setprio(0); } while (0)
; #define PG8_WAIT_V(n) asm volatile("s_waitcnt vmcnt(" #n ")" ::: "memory")
; #define PG8_WAIT_L(n) asm volatile("s_waitcnt lgkmcnt(" #n ")" ::: "memory")
; #define PG8_BAR __builtin_amdgcn_s_barrier()
; #define PG8_SCHED __builtin_amdgcn_sched_barrier(0)
; template <class Epi, class Sched>
; __device__ __forceinline__ void gemm_phase(LAS unsigned char* lds, const Gemm g, Sched S, const Epi& E) {
;     ...
;             PG8_WAIT_V(8); PG8_WAIT_L(0); PG8_BAR; PG8_MMA(1, 0, At, B0); PG8_MMA(1, 1, At, B1); PG8_BAR; PG8_SCHED;
;             PG8_LDB(B0, 1, 0); PG8_LDB(B1, 1, 1); PG8_SCHED; PG8_LDA(At, 1, 0); PG8_STAGE(PG8_SA(0, 1), a2 + hstepA, voffA);
;             PG8_WAIT_V(8); PG8_WAIT_L(0); PG8_BAR; PG8_MMA(0, 0, At, B0); PG8_MMA(0, 1, At, B1); PG8_BAR; PG8_SCHED;
	v_mfma_f32_16x16x32_bf16 v[10:13], v[150:153], v[220:223], v[10:13]
	v_mfma_f32_16x16x32_bf16 v[2:5], v[158:161], v[220:223], v[2:5]
	s_setprio 0
	s_add_i32 s3, 0, 0x18000
	s_add_i32 s71, 0, 0x1c000
	v_add_u32_e32 v142, s3, v183
	v_add_u32_e32 v158, s71, v183
	ds_read_b128 v[130:133], v142
	ds_read_b128 v[134:137], v142 offset:1024
	ds_read_b128 v[138:141], v142 offset:2048
	ds_read_b128 v[142:145], v142 offset:3072
	ds_read_b128 v[146:149], v158
	ds_read_b128 v[150:153], v158 offset:1024
	ds_read_b128 v[154:157], v158 offset:2048
	ds_read_b128 v[158:161], v158 offset:3072
	s_add_u32 s44, s44, 0x40000
	s_addc_u32 s45, s45, 0
	s_mov_b32 m0, s67
	ds_read_b128 v[174:177], v194 offset:32768
	ds_read_b128 v[196:199], v194 offset:33792
	ds_read_b128 v[200:203], v194 offset:34816
	ds_read_b128 v[204:207], v194 offset:35840
	ds_read_b128 v[208:211], v194 offset:36864
	ds_read_b128 v[212:215], v194 offset:37888
	ds_read_b128 v[216:219], v194 offset:38912
	ds_read_b128 v[220:223], v194 offset:39936
	global_load_lds_dwordx4 v168, s[44:45]
	s_mov_b32 m0, s72
	s_nop 0
	global_load_lds_dwordx4 v166, s[44:45]
	s_waitcnt vmcnt(8)
	s_waitcnt lgkmcnt(0)
	s_barrier
	s_setprio 1
	s_waitcnt lgkmcnt(0)
	v_mfma_f32_16x16x32_bf16 v[126:129], v[130:133], v[174:177], v[126:129]
	v_mfma_f32_16x16x32_bf16 v[118:121], v[138:141], v[174:177], v[118:121]
	v_mfma_f32_16x16x32_bf16 v[110:113], v[130:133], v[200:203], v[110:113]
	v_mfma_f32_16x16x32_bf16 v[102:105], v[138:141], v[200:203], v[102:105]
	v_mfma_f32_16x16x32_bf16 v[94:97], v[130:133], v[208:211], v[94:97]
	v_mfma_f32_16x16x32_bf16 v[86:89], v[138:141], v[208:211], v[86:89]
	v_mfma_f32_16x16x32_bf16 v[78:81], v[130:133], v[216:219], v[78:81]
	v_mfma_f32_16x16x32_bf16 v[70:73], v[138:141], v[216:219], v[70:73]
	v_mfma_f32_16x16x32_bf16 v[126:129], v[134:137], v[196:199], v[126:129]
	v_mfma_f32_16x16x32_bf16 v[118:121], v[142:145], v[196:199], v[118:121]
	v_mfma_f32_16x16x32_bf16 v[110:113], v[134:137], v[204:207], v[110:113]
	v_mfma_f32_16x16x32_bf16 v[102:105], v[142:145], v[204:207], v[102:105]
	v_mfma_f32_16x16x32_bf16 v[94:97], v[134:137], v[212:215], v[94:97]
	v_mfma_f32_16x16x32_bf16 v[86:89], v[142:145], v[212:215], v[86:89]
	v_mfma_f32_16x16x32_bf16 v[78:81], v[134:137], v[220:223], v[78:81]
	v_mfma_f32_16x16x32_bf16 v[70:73], v[142:145], v[220:223], v[70:73]
	s_setprio 0
	s_setprio 1
	v_mfma_f32_16x16x32_bf16 v[122:125], v[146:149], v[174:177], v[122:125]
	v_mfma_f32_16x16x32_bf16 v[114:117], v[154:157], v[174:177], v[114:117]
	v_mfma_f32_16x16x32_bf16 v[106:109], v[146:149], v[200:203], v[106:109]
	v_mfma_f32_16x16x32_bf16 v[98:101], v[154:157], v[200:203], v[98:101]
	v_mfma_f32_16x16x32_bf16 v[90:93], v[146:149], v[208:211], v[90:93]
	v_mfma_f32_16x16x32_bf16 v[82:85], v[154:157], v[208:211], v[82:85]
	v_mfma_f32_16x16x32_bf16 v[74:77], v[146:149], v[216:219], v[74:77]
	v_mfma_f32_16x16x32_bf16 v[66:69], v[154:157], v[216:219], v[66:69]
	v_mfma_f32_16x16x32_bf16 v[122:125], v[150:153], v[196:199], v[122:125]
	v_mfma_f32_16x16x32_bf16 v[114:117], v[158:161], v[196:199], v[114:117]
	v_mfma_f32_16x16x32_bf16 v[106:109], v[150:153], v[204:207], v[106:109]
	v_mfma_f32_16x16x32_bf16 v[98:101], v[158:161], v[204:207], v[98:101]
	v_mfma_f32_16x16x32_bf16 v[90:93], v[150:153], v[212:215], v[90:93]
	v_mfma_f32_16x16x32_bf16 v[82:85], v[158:161], v[212:215], v[82:85]
	s_setprio 2
	s_barrier
; #define PG8_STAGE(bufoff, gbase, voff) do { _Pragma("unroll") for (int _i = 0; _i < 2; ++_i) \
;         __builtin_amdgcn_global_load_lds((const unsigned*)((const char*)(gbase) + (voff)[_i]), (LAS unsigned*)(lds + (bufoff) + ldsw + _i * 8192), 16, 0, 0); } while (0)
; #define PG8_LDA(dst, b, h) do { _Pragma("unroll") for (int m = 0; m < 4; ++m) _Pragma("unroll") for (int k = 0; k < 2; ++k) dst[m][k] = *(const LAS bf16x8*)(lds + PG8_SA(b, h) + aoff + m * 2048 + k * 1024); } while (0)
; #define PG8_MMA(ai, bj, At, Bt) do { __builtin_amdgcn_s_setprio(1); _Pragma("unroll") for (int m = 0; m < 4; ++m) _Pragma("unroll") for (int n = 0; n < 2; ++n) _Pragma("unroll") for (int k = 0; k < 2; ++k) \
;         acc[ai][bj][m][n] = __builtin_amdgcn_mfma_f32_16x16x32_bf16(Bt[n][k], At[m][k], acc[ai][bj][m][n], 0, 0, 0); __builtin_amdgcn_s_setprio(0); } while (0)
; #define PG8_WAIT_V(n) asm volatile("s_waitcnt vmcnt(" #n ")" ::: "memory")
; #define PG8_WAIT_L(n) asm volatile("s_waitcnt lgkmcnt(" #n ")" ::: "memory")
; #define PG8_BAR __builtin_amdgcn_s_barrier()
; #define PG8_SCHED __builtin_amdgcn_sched_barrier(0)
; template <class Epi, class Sched>
; __device__ __forceinline__ void gemm_phase(LAS unsigned char* lds, const Gemm g, Sched S, const Epi& E) {
;     ...
;             PG8_WAIT_V(8); PG8_WAIT_L(0); PG8_BAR; PG8_MMA(0, 0, At, B0); PG8_MMA(0, 1, At, B1); PG8_BAR; PG8_SCHED;
;             PG8_LDA(At, 1, 1); PG8_STAGE(PG8_SB(1, 0), b3, voffB); PG8_STAGE(PG8_SB(1, 1), b3 + hstepB, voffB); PG8_STAGE(PG8_SA(1, 0), a3, voffA);
;             PG8_WAIT_V(8); PG8_WAIT_L(0); PG8_BAR; PG8_MMA(1, 0, At, B0); PG8_MMA(1, 1, At, B1); PG8_BAR; PG8_SCHED;
;         }
;         if (wr == 0) PG8_BAR;
	v_mfma_f32_16x16x32_bf16 v[74:77], v[150:153], v[220:223], v[74:77]
	v_mfma_f32_16x16x32_bf16 v[66:69], v[158:161], v[220:223], v[66:69]
	s_setprio 0
	s_add_i32 s3, s3, s7
	s_add_u32 s100, s42, 0x80
	s_addc_u32 s101, s43, 0
	s_mov_b32 m0, s3
	ds_read_b128 v[174:177], v194 offset:49152
	ds_read_b128 v[196:199], v194 offset:50176
	ds_read_b128 v[200:203], v194 offset:51200
	ds_read_b128 v[204:207], v194 offset:52224
	ds_read_b128 v[208:211], v194 offset:53248
	ds_read_b128 v[212:215], v194 offset:54272
	ds_read_b128 v[216:219], v194 offset:55296
	ds_read_b128 v[220:223], v194 offset:56320
	global_load_lds_dwordx4 v0, s[100:101]
	s_add_i32 m0, s3, 0x2000
	s_add_u32 s42, s42, 0x40080
	s_addc_u32 s43, s43, 0
	s_add_u32 s96, s44, 0xfffc0080
	s_addc_u32 s97, s45, -1
	s_add_i32 s3, s71, s7
	global_load_lds_dwordx4 v164, s[100:101]
	s_mov_b32 m0, s3
	s_nop 0
	global_load_lds_dwordx4 v0, s[42:43]
	s_add_i32 m0, s3, 0x2000
	s_nop 0
	global_load_lds_dwordx4 v164, s[42:43]
	s_mov_b32 m0, s73
	s_nop 0
	global_load_lds_dwordx4 v168, s[96:97]
	s_mov_b32 m0, s76
	s_nop 0
	global_load_lds_dwordx4 v166, s[96:97]
	s_waitcnt vmcnt(8)
	s_waitcnt lgkmcnt(0)
	s_barrier
	s_setprio 1
	s_waitcnt lgkmcnt(0)
	v_mfma_f32_16x16x32_bf16 v[62:65], v[130:133], v[174:177], v[62:65]
	v_mfma_f32_16x16x32_bf16 v[54:57], v[138:141], v[174:177], v[54:57]
	v_mfma_f32_16x16x32_bf16 v[46:49], v[130:133], v[200:203], v[46:49]
	v_mfma_f32_16x16x32_bf16 v[38:41], v[138:141], v[200:203], v[38:41]
	v_mfma_f32_16x16x32_bf16 v[30:33], v[130:133], v[208:211], v[30:33]
	v_mfma_f32_16x16x32_bf16 v[22:25], v[138:141], v[208:211], v[22:25]
	v_mfma_f32_16x16x32_bf16 v[14:17], v[130:133], v[216:219], v[14:17]
	v_mfma_f32_16x16x32_bf16 v[6:9], v[138:141], v[216:219], v[6:9]
	v_mfma_f32_16x16x32_bf16 v[62:65], v[134:137], v[196:199], v[62:65]
	v_mfma_f32_16x16x32_bf16 v[54:57], v[142:145], v[196:199], v[54:57]
	v_mfma_f32_16x16x32_bf16 v[46:49], v[134:137], v[204:207], v[46:49]
	v_mfma_f32_16x16x32_bf16 v[38:41], v[142:145], v[204:207], v[38:41]
	v_mfma_f32_16x16x32_bf16 v[30:33], v[134:137], v[212:215], v[30:33]
	v_mfma_f32_16x16x32_bf16 v[22:25], v[142:145], v[212:215], v[22:25]
	v_mfma_f32_16x16x32_bf16 v[14:17], v[134:137], v[220:223], v[14:17]
	v_mfma_f32_16x16x32_bf16 v[6:9], v[142:145], v[220:223], v[6:9]
	s_setprio 0
	s_setprio 1
	v_mfma_f32_16x16x32_bf16 v[58:61], v[146:149], v[174:177], v[58:61]
	v_mfma_f32_16x16x32_bf16 v[50:53], v[154:157], v[174:177], v[50:53]
	v_mfma_f32_16x16x32_bf16 v[42:45], v[146:149], v[200:203], v[42:45]
	v_mfma_f32_16x16x32_bf16 v[34:37], v[154:157], v[200:203], v[34:37]
	v_mfma_f32_16x16x32_bf16 v[26:29], v[146:149], v[208:211], v[26:29]
	v_mfma_f32_16x16x32_bf16 v[18:21], v[154:157], v[208:211], v[18:21]
	v_mfma_f32_16x16x32_bf16 v[10:13], v[146:149], v[216:219], v[10:13]
	v_mfma_f32_16x16x32_bf16 v[2:5], v[154:157], v[216:219], v[2:5]
	v_mfma_f32_16x16x32_bf16 v[58:61], v[150:153], v[196:199], v[58:61]
	v_mfma_f32_16x16x32_bf16 v[50:53], v[158:161], v[196:199], v[50:53]
	v_mfma_f32_16x16x32_bf16 v[42:45], v[150:153], v[204:207], v[42:45]
	v_mfma_f32_16x16x32_bf16 v[34:37], v[158:161], v[204:207], v[34:37]
	v_mfma_f32_16x16x32_bf16 v[26:29], v[150:153], v[212:215], v[26:29]
	v_mfma_f32_16x16x32_bf16 v[18:21], v[158:161], v[212:215], v[18:21]
	s_setprio 2
	s_barrier
	v_mfma_f32_16x16x32_bf16 v[10:13], v[150:153], v[220:223], v[10:13]
	v_mfma_f32_16x16x32_bf16 v[2:5], v[158:161], v[220:223], v[2:5]
	s_setprio 0
	s_add_i32 s70, s70, 2
	s_add_u32 s64, s64, 0x100
	s_addc_u32 s65, s65, 0
	s_add_u32 s10, s10, 0x100
	s_addc_u32 s11, s11, 0
	s_cmp_gt_u32 s70, 13
	s_cbranch_scc0 .LBB0_770
	s_and_b64 vcc, exec, s[30:31]
	s_cbranch_vccz .LBB0_773
	s_barrier
